# phase-4 SwiGLU epilogue: 8 row-statistics pairs preloaded at epilogue start, rstd via v_rsq_f32
# speedup vs baseline: 1.0077x; 1.0077x over previous
; __device__ __forceinline__ u32x4 pack8bf(const f32x4 a, const f32x4 b) { u32x4 w; w.x = cvt_pk_bf16(a[0], a[1]); w.y = cvt_pk_bf16(a[2], a[3]); w.z = cvt_pk_bf16(b[0], b[1]); w.w = cvt_pk_bf16(b[2], b[3]); return w; }
; __device__ __forceinline__ void ln_stats(const float* st, int row, float& mu, float& rs) { const f32x2 s = *(const f32x2*)(st + 2 * (size_t)row); mu = s[0] * (1.0f / DM); rs = 1.0f / sqrtf(s[1] * (1.0f / DM) - mu * mu + LN_EPS); }
;     __device__ __forceinline__ void operator()(EPI_ARGS) const {
;         const int row0 = u.pm * BM + wr * 64 + fr, col0 = u.pn * HALF + wc * 32 + 8 * fq, n0 = u.pn * BM + wc * 32 + 8 * fq;
;         f32x4 cg[2], dg[2], cu[2], du[2];
;         if constexpr (FOLD) {
; #pragma unroll
;             for (int n = 0; n < 2; ++n) { cg[n] = *(const f32x4*)(C + n0 + 4 * n); dg[n] = *(const f32x4*)(D + n0 + 4 * n); cu[n] = *(const f32x4*)(C + n0 + HALF + 4 * n); du[n] = *(const f32x4*)(D + n0 + HALF + 4 * n);
;                 if constexpr (PRE) { float os_ = oscale; asm volatile("" : "+s"(os_)); cu[n] = cu[n] * os_; du[n] = du[n] * os_; } } }
; #pragma unroll
;         for (int ai = 0; ai < 2; ++ai)
; #pragma unroll
;             for (int m = 0; m < 4; ++m) { const int row = row0 + ai * HALF + m * 16; f32x4 r[2];
;                 float mu = 0.f, rs = 1.f; if constexpr (FOLD) ln_stats(st, row, mu, rs);
; #pragma unroll
;                 for (int n = 0; n < 2; ++n) { f32x4 g = acc[ai][0][m][n], up = acc[ai][1][m][n];
;                     if constexpr (!PRE) { g = g * ascale; up = up * ascale; }
;                     if constexpr (FOLD) { g = (g - cg[n] * mu) * rs + dg[n]; up = (up - cu[n] * mu) * rs + du[n]; }
;                     if constexpr (!PRE) up = up * oscale;
; #pragma unroll
;                     for (int j = 0; j < 4; ++j) { const float e = __builtin_amdgcn_exp2f(g[j] * -1.4426950408889634f); r[n][j] = g[j] * __builtin_amdgcn_rcpf(1.0f + e) * up[j]; } }
;                 if constexpr (F8OUT) *(u32x2*)((unsigned char*)O + (size_t)row * ldc + col0) = pack8fp8(r[0], r[1]);
;                 else *(u32x4*)((bf16_t*)O + (size_t)row * ldc + col0) = pack8bf(r[0], r[1]); }
;     }
.LBB0_3779:
	v_lshl_or_b32 v84, s5, 8, v168
	v_lshl_add_u32 v160, s4, 8, v166
	v_ashrrev_i32_e32 v85, 31, v84
	v_lshlrev_b64 v[84:85], 2, v[84:85]
	v_ashrrev_i32_e32 v161, 31, v160
	v_lshl_add_u64 v[88:89], s[8:9], 0, v[84:85]
	v_lshl_add_u64 v[182:183], s[10:11], 0, v[84:85]
	s_mov_b32 s4, 0x41800000
	s_mov_b32 s40, 0x41800000
	v_lshl_add_u64 v[186:187], v[160:161], 3, s[14:15]
	global_load_dwordx4 v[96:99], v[88:89], off
	global_load_dwordx4 v[162:165], v[88:89], off offset:512
	global_load_dwordx4 v[100:103], v[182:183], off
	global_load_dwordx4 v[174:177], v[182:183], off offset:512
	global_load_dwordx4 v[84:87], v[88:89], off offset:16
	global_load_dwordx4 v[178:181], v[88:89], off offset:528
	s_nop 0
	global_load_dwordx4 v[88:91], v[182:183], off offset:16
	s_nop 0
	global_load_dwordx4 v[182:185], v[182:183], off offset:528
	global_load_dwordx2 v[226:227], v[186:187], off offset:128
	global_load_dwordx2 v[228:229], v[186:187], off offset:256
	global_load_dwordx2 v[230:231], v[186:187], off offset:384
	global_load_dwordx2 v[232:233], v[186:187], off offset:1024
	global_load_dwordx2 v[234:235], v[186:187], off offset:1152
	global_load_dwordx2 v[236:237], v[186:187], off offset:1280
	global_load_dwordx2 v[238:239], v[186:187], off offset:1408
	global_load_dwordx2 v[186:187], v[186:187], off
	v_cvt_f32_i32_e32 v131, v131
	v_cvt_f32_i32_e32 v130, v130
	v_cvt_f32_i32_e32 v137, v137
	v_cvt_f32_i32_e32 v136, v136
	v_cvt_f32_i32_e32 v141, v141
	v_pk_mul_f32 v[194:195], v[130:131], s[24:25] op_sel_hi:[1,0]
	v_cvt_f32_i32_e32 v140, v140
	v_cvt_f32_i32_e32 v133, v133
	v_cvt_f32_i32_e32 v132, v132
	v_pk_mul_f32 v[192:193], v[136:137], s[20:21] op_sel_hi:[1,0]
	v_cvt_f32_i32_e32 v139, v139
	v_cvt_f32_i32_e32 v138, v138
	v_cvt_f32_i32_e32 v135, v135
	v_cvt_f32_i32_e32 v134, v134
	v_pk_mul_f32 v[140:141], v[140:141], s[20:21] op_sel_hi:[1,0]
	v_pk_mul_f32 v[132:133], v[132:133], s[24:25] op_sel_hi:[1,0]
	v_pk_mul_f32 v[190:191], v[138:139], s[20:21] op_sel_hi:[1,0]
	v_pk_mul_f32 v[134:135], v[134:135], s[24:25] op_sel_hi:[1,0]
	v_mov_b32_e32 v138, v132
	v_mov_b32_e32 v139, v140
	v_mov_b32_e32 v140, v133
	v_cvt_f32_i32_e32 v188, v128
	v_lshl_or_b32 v128, s5, 7, v168
	v_mov_b32_e32 v196, v134
	v_cvt_f32_i32_e32 v143, v143
	v_cvt_f32_i32_e32 v142, v142
	v_cvt_f32_i32_e32 v189, v129
	v_ashrrev_i32_e32 v129, 31, v128
	v_cvt_f32_i32_e32 v125, v125
	v_pk_mul_f32 v[142:143], v[142:143], s[20:21] op_sel_hi:[1,0]
	v_pk_mul_f32 v[188:189], v[188:189], s[24:25] op_sel_hi:[1,0]
	v_mov_b32_e32 v197, v142
	v_mov_b32_e32 v142, v135
	v_cvt_f32_i32_e32 v124, v124
	v_cvt_f32_i32_e32 v117, v117
	v_cvt_f32_i32_e32 v116, v116
	v_cvt_f32_i32_e32 v127, v127
	v_pk_mul_f32 v[124:125], v[124:125], s[20:21] op_sel_hi:[1,0]
	v_cvt_f32_i32_e32 v126, v126
	v_pk_mul_f32 v[116:117], v[116:117], s[24:25] op_sel_hi:[1,0]
	v_cvt_f32_i32_e32 v119, v119
	v_cvt_f32_i32_e32 v118, v118
	v_pk_mul_f32 v[126:127], v[126:127], s[20:21] op_sel_hi:[1,0]
	v_cvt_f32_i32_e32 v121, v121
	v_cvt_f32_i32_e32 v120, v120
	v_pk_mul_f32 v[118:119], v[118:119], s[24:25] op_sel_hi:[1,0]
	v_cvt_f32_i32_e32 v113, v113
	v_cvt_f32_i32_e32 v112, v112
	v_pk_mul_f32 v[120:121], v[120:121], s[20:21] op_sel_hi:[1,0]
	v_cvt_f32_i32_e32 v123, v123
	v_cvt_f32_i32_e32 v122, v122
	v_pk_mul_f32 v[112:113], v[112:113], s[24:25] op_sel_hi:[1,0]
	v_cvt_f32_i32_e32 v115, v115
	v_cvt_f32_i32_e32 v114, v114
	v_pk_mul_f32 v[122:123], v[122:123], s[20:21] op_sel_hi:[1,0]
	v_cvt_f32_i32_e32 v109, v109
	v_cvt_f32_i32_e32 v108, v108
	v_pk_mul_f32 v[114:115], v[114:115], s[24:25] op_sel_hi:[1,0]
	v_cvt_f32_i32_e32 v93, v93
	v_cvt_f32_i32_e32 v92, v92
	v_pk_mul_f32 v[108:109], v[108:109], s[20:21] op_sel_hi:[1,0]
	v_cvt_f32_i32_e32 v111, v111
	v_cvt_f32_i32_e32 v110, v110
	v_pk_mul_f32 v[92:93], v[92:93], s[24:25] op_sel_hi:[1,0]
	v_cvt_f32_i32_e32 v95, v95
	v_cvt_f32_i32_e32 v94, v94
	v_pk_mul_f32 v[110:111], v[110:111], s[20:21] op_sel_hi:[1,0]
	v_cvt_f32_i32_e32 v105, v105
	v_cvt_f32_i32_e32 v104, v104
	v_pk_mul_f32 v[94:95], v[94:95], s[24:25] op_sel_hi:[1,0]
	v_cvt_f32_i32_e32 v81, v81
	v_cvt_f32_i32_e32 v80, v80
	s_waitcnt vmcnt(0)
	v_mov_b32_e32 v137, v96
	v_pk_mul_f32 v[162:163], v[162:163], s[4:5] op_sel_hi:[1,0]
	v_mov_b32_e32 v131, v102
	v_mov_b32_e32 v136, v162
	v_pk_mul_f32 v[164:165], v[164:165], s[4:5] op_sel_hi:[1,0]
	v_mov_b32_e32 v96, v163
	v_pk_mul_f32 v[174:175], v[174:175], s[4:5] op_sel_hi:[1,0]
	v_pk_mul_f32 v[186:187], v[186:187], s[26:27] op_sel_hi:[1,0]
	v_mov_b32_e32 v133, v98
	v_fma_f32 v102, -v186, v186, v187
	v_add_f32_e32 v102, 0x3727c5ac, v102
	v_rsq_f32_e32 v242, v102
	v_mov_b32_e32 v132, v164
	v_mov_b32_e32 v98, v165
	v_pk_mul_f32 v[176:177], v[176:177], s[4:5] op_sel_hi:[1,0]
	v_mov_b32_e32 v134, v174
	v_mov_b32_e32 v135, v100
	v_mov_b32_e32 v100, v175
	v_mov_b32_e32 v130, v176
	v_pk_fma_f32 v[138:139], v[136:137], v[186:187], v[138:139] op_sel_hi:[1,0,1] neg_lo:[1,0,0] neg_hi:[1,0,0]
	v_pk_fma_f32 v[140:141], v[96:97], v[186:187], v[140:141] op_sel_hi:[1,0,1] neg_lo:[1,0,0] neg_hi:[1,0,0]
	v_mov_b32_e32 v102, v177
	v_pk_fma_f32 v[142:143], v[98:99], v[186:187], v[142:143] op_sel_hi:[1,0,1] neg_lo:[1,0,0] neg_hi:[1,0,0]
	v_pk_fma_f32 v[162:163], v[132:133], v[186:187], v[196:197] op_sel_hi:[1,0,1] neg_lo:[1,0,0] neg_hi:[1,0,0]
	v_mov_b32_e32 v164, v242
	v_pk_fma_f32 v[138:139], v[138:139], v[164:165], v[134:135] op_sel_hi:[1,0,1]
	v_pk_fma_f32 v[140:141], v[140:141], v[164:165], v[100:101] op_sel_hi:[1,0,1]
	v_mul_f32_e32 v161, 0xbfb8aa3b, v139
	v_mul_f32_e32 v165, 0xbfb8aa3b, v141
	v_exp_f32_e32 v161, v161
	v_exp_f32_e32 v165, v165
	v_pk_mul_f32 v[178:179], v[178:179], s[40:41] op_sel_hi:[1,0]
; __device__ __forceinline__ u32x4 pack8bf(const f32x4 a, const f32x4 b) { u32x4 w; w.x = cvt_pk_bf16(a[0], a[1]); w.y = cvt_pk_bf16(a[2], a[3]); w.z = cvt_pk_bf16(b[0], b[1]); w.w = cvt_pk_bf16(b[2], b[3]); return w; }
;     __device__ __forceinline__ float qscale(const Unit& u) const { return ((u.pn >= 8 && u.pn <= 11) || u.pn == 17) ? 0.5f : 1.0f; }
; __device__ __forceinline__ void ln_stats(const float* st, int row, float& mu, float& rs) { const f32x2 s = *(const f32x2*)(st + 2 * (size_t)row); mu = s[0] * (1.0f / DM); rs = 1.0f / sqrtf(s[1] * (1.0f / DM) - mu * mu + LN_EPS); }
;     ...
;         if constexpr (QM == 2) { const float qs0_ = g.qs * E.qscale(cur), qs1_ = qs0_ * g.qs_b1; _Pragma("unroll") for (int a = 0; a < 2; ++a) _Pragma("unroll") for (int b = 0; b < 2; ++b) _Pragma("unroll") for (int m = 0; m < 4; ++m) _Pragma("unroll") for (int n = 0; n < 2; ++n) { const v4i t_ = __builtin_bit_cast(v4i, acc[a][b][m][n]); acc[a][b][m][n] = (f32x4){(float)t_[0], (float)t_[1], (float)t_[2], (float)t_[3]} * (b == 0 ? qs0_ : qs1_); } }
;     __device__ __forceinline__ void operator()(EPI_ARGS) const {
;     ...
;             for (int m = 0; m < 4; ++m) { const int row = row0 + ai * HALF + m * 16; f32x4 r[2];
;                 float mu = 0.f, rs = 1.f; if constexpr (FOLD) ln_stats(st, row, mu, rs);
; #pragma unroll
;                 for (int n = 0; n < 2; ++n) { f32x4 g = acc[ai][0][m][n], up = acc[ai][1][m][n];
;                     if constexpr (!PRE) { g = g * ascale; up = up * ascale; }
;                     if constexpr (FOLD) { g = (g - cg[n] * mu) * rs + dg[n]; up = (up - cu[n] * mu) * rs + du[n]; }
;                     if constexpr (!PRE) up = up * oscale;
; #pragma unroll
;                     for (int j = 0; j < 4; ++j) { const float e = __builtin_amdgcn_exp2f(g[j] * -1.4426950408889634f); r[n][j] = g[j] * __builtin_amdgcn_rcpf(1.0f + e) * up[j]; } }
;                 if constexpr (F8OUT) *(u32x2*)((unsigned char*)O + (size_t)row * ldc + col0) = pack8fp8(r[0], r[1]);
;                 else *(u32x4*)((bf16_t*)O + (size_t)row * ldc + col0) = pack8bf(r[0], r[1]); }
	v_pk_mul_f32 v[182:183], v[182:183], s[40:41] op_sel_hi:[1,0]
	v_add_f32_e32 v161, 1.0, v161
	v_pk_fma_f32 v[162:163], v[162:163], v[164:165], v[130:131] op_sel_hi:[1,0,1]
	v_add_f32_e32 v165, 1.0, v165
	v_rcp_f32_e32 v161, v161
	v_rcp_f32_e32 v165, v165
	v_mul_f32_e32 v174, 0xbfb8aa3b, v163
	v_exp_f32_e32 v174, v174
	v_mul_f32_e32 v139, v139, v161
	v_pk_fma_f32 v[142:143], v[142:143], v[164:165], v[102:103] op_sel_hi:[1,0,1]
	v_mul_f32_e32 v161, v138, v139
	v_mul_f32_e32 v138, 0xbfb8aa3b, v143
	v_exp_f32_e32 v138, v138
	v_add_f32_e32 v139, 1.0, v174
	v_mul_f32_e32 v141, v141, v165
	v_rcp_f32_e32 v165, v139
	v_add_f32_e32 v138, 1.0, v138
	v_mul_f32_e32 v196, v140, v141
	v_rcp_f32_e32 v176, v138
	v_mov_b32_e32 v138, v178
	v_mov_b32_e32 v139, v84
	v_mov_b32_e32 v140, v188
	v_mov_b32_e32 v141, v192
	v_pk_fma_f32 v[174:175], v[186:187], v[138:139], v[140:141] op_sel_hi:[0,1,1] neg_lo:[1,0,0] neg_hi:[1,0,0]
	v_mov_b32_e32 v140, v182
	v_mov_b32_e32 v141, v88
	v_pk_fma_f32 v[174:175], v[174:175], v[164:165], v[140:141] op_sel_hi:[1,0,1]
	v_mul_f32_e32 v88, v163, v165
	v_mul_f32_e32 v84, 0xbfb8aa3b, v175
	v_exp_f32_e32 v84, v84
	v_mov_b32_e32 v192, v189
	v_mul_f32_e32 v182, v162, v88
	v_mov_b32_e32 v88, v183
	v_add_f32_e32 v84, 1.0, v84
	v_rcp_f32_e32 v165, v84
	v_mov_b32_e32 v84, v179
	v_pk_fma_f32 v[162:163], v[186:187], v[84:85], v[192:193] op_sel_hi:[0,1,1] neg_lo:[1,0,0] neg_hi:[1,0,0]
	v_mul_f32_e32 v143, v143, v176
	v_pk_fma_f32 v[176:177], v[162:163], v[164:165], v[88:89] op_sel_hi:[1,0,1]
	v_mul_f32_e32 v183, v142, v143
	v_mul_f32_e32 v162, 0xbfb8aa3b, v177
	v_exp_f32_e32 v162, v162
	v_mul_f32_e32 v142, v175, v165
	v_pk_mul_f32 v[180:181], v[180:181], s[40:41] op_sel_hi:[1,0]
	v_mul_f32_e32 v188, v174, v142
	v_add_f32_e32 v142, 1.0, v162
	v_pk_mul_f32 v[184:185], v[184:185], s[40:41] op_sel_hi:[1,0]
	v_rcp_f32_e32 v189, v142
	v_mov_b32_e32 v142, v180
	v_mov_b32_e32 v143, v86
	v_mov_b32_e32 v162, v194
	v_mov_b32_e32 v163, v190
	v_pk_fma_f32 v[174:175], v[186:187], v[142:143], v[162:163] op_sel_hi:[0,1,1] neg_lo:[1,0,0] neg_hi:[1,0,0]
	v_mov_b32_e32 v162, v184
	v_mov_b32_e32 v163, v90
	v_pk_fma_f32 v[174:175], v[174:175], v[164:165], v[162:163] op_sel_hi:[1,0,1]
	v_mov_b32_e32 v190, v195
	v_mul_f32_e32 v86, 0xbfb8aa3b, v175
	v_exp_f32_e32 v180, v86
	v_mov_b32_e32 v86, v181
	v_pk_fma_f32 v[178:179], v[186:187], v[86:87], v[190:191] op_sel_hi:[0,1,1] neg_lo:[1,0,0] neg_hi:[1,0,0]
	v_mov_b32_e32 v90, v185
	v_pk_fma_f32 v[164:165], v[178:179], v[164:165], v[90:91] op_sel_hi:[1,0,1]
	v_add_f32_e32 v179, 1.0, v180
	v_mul_f32_e32 v178, 0xbfb8aa3b, v165
	v_exp_f32_e32 v178, v178
	v_rcp_f32_e32 v179, v179
	v_mul_f32_e32 v177, v177, v189
	v_mul_f32_e32 v176, v176, v177
	v_add_f32_e32 v178, 1.0, v178
	v_rcp_f32_e32 v178, v178
	v_mul_f32_e32 v175, v175, v179
	v_mul_f32_e32 v177, v174, v175
	v_med3_f32 v161, v161, s62, v173
	v_mul_f32_e32 v165, v165, v178
	v_mul_f32_e32 v164, v164, v165
	v_med3_f32 v165, v196, s62, v173
	v_mov_b32_e32 v174, 0
	v_cvt_pk_fp8_f32 v174, v161, v165
	v_med3_f32 v178, v188, s62, v173
	v_med3_f32 v176, v176, s62, v173
	v_mov_b32_e32 v175, 0
	v_cvt_pk_fp8_f32 v175, v178, v176
	v_med3_f32 v161, v182, s62, v173
	v_med3_f32 v165, v183, s62, v173
	v_cvt_pk_fp8_f32 v174, v161, v165 op_sel:[0,0,1]
	v_med3_f32 v161, v177, s62, v173
	v_med3_f32 v164, v164, s62, v173
	v_cvt_pk_fp8_f32 v175, v161, v164 op_sel:[0,0,1]
	v_mov_b64_e32 v[164:165], s[12:13]
	v_mad_i64_i32 v[176:177], s[4:5], v160, s63, v[164:165]
	v_lshl_add_u64 v[176:177], v[176:177], 0, v[128:129]
	global_store_dwordx2 v[176:177], v[174:175], off
	v_or_b32_e32 v174, 16, v160
	v_ashrrev_i32_e32 v175, 31, v174
	v_lshl_add_u64 v[176:177], v[174:175], 3, s[14:15]
	v_mov_b32_e32 v176, v226
	v_mov_b32_e32 v177, v227
	v_pk_mul_f32 v[104:105], v[104:105], s[20:21] op_sel_hi:[1,0]
	v_pk_mul_f32 v[80:81], v[80:81], s[24:25] op_sel_hi:[1,0]
	v_cvt_f32_i32_e32 v107, v107
	v_cvt_f32_i32_e32 v106, v106
	v_cvt_f32_i32_e32 v83, v83
	v_cvt_f32_i32_e32 v82, v82
	v_cvt_f32_i32_e32 v77, v77
	v_pk_mul_f32 v[106:107], v[106:107], s[20:21] op_sel_hi:[1,0]
	v_cvt_f32_i32_e32 v76, v76
	v_pk_mul_f32 v[82:83], v[82:83], s[24:25] op_sel_hi:[1,0]
	v_cvt_f32_i32_e32 v69, v69
	v_cvt_f32_i32_e32 v68, v68
	v_pk_mul_f32 v[76:77], v[76:77], s[20:21] op_sel_hi:[1,0]
	v_cvt_f32_i32_e32 v79, v79
	v_cvt_f32_i32_e32 v78, v78
	v_pk_mul_f32 v[68:69], v[68:69], s[24:25] op_sel_hi:[1,0]
	v_cvt_f32_i32_e32 v71, v71
	v_cvt_f32_i32_e32 v70, v70
	v_pk_mul_f32 v[78:79], v[78:79], s[20:21] op_sel_hi:[1,0]
	v_cvt_f32_i32_e32 v73, v73
	v_cvt_f32_i32_e32 v72, v72
	v_pk_mul_f32 v[70:71], v[70:71], s[24:25] op_sel_hi:[1,0]
	v_cvt_f32_i32_e32 v65, v65
	v_cvt_f32_i32_e32 v64, v64
	v_pk_mul_f32 v[72:73], v[72:73], s[20:21] op_sel_hi:[1,0]
	v_cvt_f32_i32_e32 v75, v75
	v_cvt_f32_i32_e32 v74, v74
	v_pk_mul_f32 v[64:65], v[64:65], s[24:25] op_sel_hi:[1,0]
	v_cvt_f32_i32_e32 v67, v67
	v_cvt_f32_i32_e32 v66, v66
	v_pk_mul_f32 v[74:75], v[74:75], s[20:21] op_sel_hi:[1,0]
	v_cvt_f32_i32_e32 v61, v61
	v_cvt_f32_i32_e32 v60, v60
	v_pk_mul_f32 v[66:67], v[66:67], s[24:25] op_sel_hi:[1,0]
	v_cvt_f32_i32_e32 v53, v53
	v_cvt_f32_i32_e32 v52, v52
	v_pk_mul_f32 v[60:61], v[60:61], s[20:21] op_sel_hi:[1,0]
	v_cvt_f32_i32_e32 v63, v63
	v_cvt_f32_i32_e32 v62, v62
	v_pk_mul_f32 v[52:53], v[52:53], s[24:25] op_sel_hi:[1,0]
	v_cvt_f32_i32_e32 v55, v55
	v_cvt_f32_i32_e32 v54, v54
	v_pk_mul_f32 v[62:63], v[62:63], s[20:21] op_sel_hi:[1,0]
	v_cvt_f32_i32_e32 v57, v57
	v_cvt_f32_i32_e32 v56, v56
	v_pk_mul_f32 v[54:55], v[54:55], s[24:25] op_sel_hi:[1,0]
	v_cvt_f32_i32_e32 v49, v49
	v_cvt_f32_i32_e32 v48, v48
	v_pk_mul_f32 v[56:57], v[56:57], s[20:21] op_sel_hi:[1,0]
; __device__ __forceinline__ u32x4 pack8bf(const f32x4 a, const f32x4 b) { u32x4 w; w.x = cvt_pk_bf16(a[0], a[1]); w.y = cvt_pk_bf16(a[2], a[3]); w.z = cvt_pk_bf16(b[0], b[1]); w.w = cvt_pk_bf16(b[2], b[3]); return w; }
; __device__ __forceinline__ void ln_stats(const float* st, int row, float& mu, float& rs) { const f32x2 s = *(const f32x2*)(st + 2 * (size_t)row); mu = s[0] * (1.0f / DM); rs = 1.0f / sqrtf(s[1] * (1.0f / DM) - mu * mu + LN_EPS); }
;     __device__ __forceinline__ void operator()(EPI_ARGS) const {
;     ...
;             for (int m = 0; m < 4; ++m) { const int row = row0 + ai * HALF + m * 16; f32x4 r[2];
;                 float mu = 0.f, rs = 1.f; if constexpr (FOLD) ln_stats(st, row, mu, rs);
; #pragma unroll
;                 for (int n = 0; n < 2; ++n) { f32x4 g = acc[ai][0][m][n], up = acc[ai][1][m][n];
;                     if constexpr (!PRE) { g = g * ascale; up = up * ascale; }
;                     if constexpr (FOLD) { g = (g - cg[n] * mu) * rs + dg[n]; up = (up - cu[n] * mu) * rs + du[n]; }
;                     if constexpr (!PRE) up = up * oscale;
; #pragma unroll
;                     for (int j = 0; j < 4; ++j) { const float e = __builtin_amdgcn_exp2f(g[j] * -1.4426950408889634f); r[n][j] = g[j] * __builtin_amdgcn_rcpf(1.0f + e) * up[j]; } }
;                 if constexpr (F8OUT) *(u32x2*)((unsigned char*)O + (size_t)row * ldc + col0) = pack8fp8(r[0], r[1]);
;                 else *(u32x4*)((bf16_t*)O + (size_t)row * ldc + col0) = pack8bf(r[0], r[1]); }
	v_cvt_f32_i32_e32 v59, v59
	v_cvt_f32_i32_e32 v58, v58
	v_pk_mul_f32 v[48:49], v[48:49], s[24:25] op_sel_hi:[1,0]
	v_cvt_f32_i32_e32 v51, v51
	v_cvt_f32_i32_e32 v50, v50
	v_pk_mul_f32 v[58:59], v[58:59], s[20:21] op_sel_hi:[1,0]
	v_cvt_f32_i32_e32 v45, v45
	v_cvt_f32_i32_e32 v44, v44
	v_pk_mul_f32 v[50:51], v[50:51], s[24:25] op_sel_hi:[1,0]
	v_cvt_f32_i32_e32 v37, v37
	v_cvt_f32_i32_e32 v36, v36
	v_pk_mul_f32 v[44:45], v[44:45], s[20:21] op_sel_hi:[1,0]
	v_cvt_f32_i32_e32 v47, v47
	v_cvt_f32_i32_e32 v46, v46
	v_pk_mul_f32 v[36:37], v[36:37], s[24:25] op_sel_hi:[1,0]
	v_cvt_f32_i32_e32 v39, v39
	v_cvt_f32_i32_e32 v38, v38
	v_pk_mul_f32 v[46:47], v[46:47], s[20:21] op_sel_hi:[1,0]
	v_cvt_f32_i32_e32 v41, v41
	v_cvt_f32_i32_e32 v40, v40
	v_pk_mul_f32 v[38:39], v[38:39], s[24:25] op_sel_hi:[1,0]
	v_cvt_f32_i32_e32 v33, v33
	v_cvt_f32_i32_e32 v32, v32
	v_pk_mul_f32 v[40:41], v[40:41], s[20:21] op_sel_hi:[1,0]
	v_cvt_f32_i32_e32 v43, v43
	v_cvt_f32_i32_e32 v42, v42
	v_pk_mul_f32 v[32:33], v[32:33], s[24:25] op_sel_hi:[1,0]
	v_cvt_f32_i32_e32 v35, v35
	v_cvt_f32_i32_e32 v34, v34
	v_pk_mul_f32 v[42:43], v[42:43], s[20:21] op_sel_hi:[1,0]
	v_pk_mul_f32 v[176:177], v[176:177], s[26:27] op_sel_hi:[1,0]
	v_cvt_f32_i32_e32 v29, v29
	v_fma_f32 v161, -v176, v176, v177
	v_add_f32_e32 v161, 0x3727c5ac, v161
	v_rsq_f32_e32 v242, v161
	v_pk_mul_f32 v[34:35], v[34:35], s[24:25] op_sel_hi:[1,0]
	v_cvt_f32_i32_e32 v28, v28
	v_cvt_f32_i32_e32 v21, v21
	v_cvt_f32_i32_e32 v20, v20
	v_pk_mul_f32 v[28:29], v[28:29], s[20:21] op_sel_hi:[1,0]
	v_pk_mul_f32 v[20:21], v[20:21], s[24:25] op_sel_hi:[1,0]
	v_cvt_f32_i32_e32 v31, v31
	v_cvt_f32_i32_e32 v30, v30
	v_cvt_f32_i32_e32 v23, v23
	v_cvt_f32_i32_e32 v22, v22
	v_pk_mul_f32 v[30:31], v[30:31], s[20:21] op_sel_hi:[1,0]
	v_pk_mul_f32 v[22:23], v[22:23], s[24:25] op_sel_hi:[1,0]
	v_cvt_f32_i32_e32 v25, v25
	v_mov_b32_e32 v180, v116
	v_mov_b32_e32 v181, v124
	v_mov_b32_e32 v178, v242
	v_pk_fma_f32 v[180:181], v[136:137], v[176:177], v[180:181] op_sel_hi:[1,0,1] neg_lo:[1,0,0] neg_hi:[1,0,0]
	v_mov_b32_e32 v124, v117
	v_pk_fma_f32 v[180:181], v[180:181], v[178:179], v[134:135] op_sel_hi:[1,0,1]
	v_cvt_f32_i32_e32 v24, v24
	v_mul_f32_e32 v116, 0xbfb8aa3b, v181
	v_exp_f32_e32 v161, v116
	v_pk_fma_f32 v[116:117], v[96:97], v[176:177], v[124:125] op_sel_hi:[1,0,1] neg_lo:[1,0,0] neg_hi:[1,0,0]
	v_cvt_f32_i32_e32 v17, v17
	v_pk_fma_f32 v[116:117], v[116:117], v[178:179], v[100:101] op_sel_hi:[1,0,1]
	v_add_f32_e32 v125, 1.0, v161
	v_mul_f32_e32 v124, 0xbfb8aa3b, v117
	v_exp_f32_e32 v124, v124
	v_rcp_f32_e32 v125, v125
	v_cvt_f32_i32_e32 v16, v16
	v_pk_mul_f32 v[24:25], v[24:25], s[20:21] op_sel_hi:[1,0]
	v_add_f32_e32 v124, 1.0, v124
	v_rcp_f32_e32 v124, v124
	v_mul_f32_e32 v125, v181, v125
	v_mul_f32_e32 v161, v180, v125
	v_mov_b32_e32 v125, v126
	v_mul_f32_e32 v117, v117, v124
	v_mov_b32_e32 v124, v118
	v_pk_fma_f32 v[124:125], v[132:133], v[176:177], v[124:125] op_sel_hi:[1,0,1] neg_lo:[1,0,0] neg_hi:[1,0,0]
	v_mov_b32_e32 v126, v119
	v_pk_fma_f32 v[124:125], v[124:125], v[178:179], v[130:131] op_sel_hi:[1,0,1]
	v_pk_mul_f32 v[16:17], v[16:17], s[24:25] op_sel_hi:[1,0]
	v_mul_f32_e32 v118, 0xbfb8aa3b, v125
	v_exp_f32_e32 v175, v118
	v_pk_fma_f32 v[118:119], v[98:99], v[176:177], v[126:127] op_sel_hi:[1,0,1] neg_lo:[1,0,0] neg_hi:[1,0,0]
	v_mul_f32_e32 v127, v116, v117
	v_pk_fma_f32 v[118:119], v[118:119], v[178:179], v[102:103] op_sel_hi:[1,0,1]
	v_add_f32_e32 v116, 1.0, v175
	v_mul_f32_e32 v126, 0xbfb8aa3b, v119
	v_exp_f32_e32 v126, v126
	v_rcp_f32_e32 v175, v116
	v_mov_b32_e32 v117, v120
	v_cvt_f32_i32_e32 v27, v27
	v_add_f32_e32 v116, 1.0, v126
	v_rcp_f32_e32 v126, v116
	v_mov_b32_e32 v116, v112
	v_pk_fma_f32 v[116:117], v[138:139], v[176:177], v[116:117] op_sel_hi:[1,0,1] neg_lo:[1,0,0] neg_hi:[1,0,0]
	v_mul_f32_e32 v120, v125, v175
	v_pk_fma_f32 v[116:117], v[116:117], v[178:179], v[140:141] op_sel_hi:[1,0,1]
	v_mul_f32_e32 v124, v124, v120
	v_mul_f32_e32 v112, 0xbfb8aa3b, v117
	v_exp_f32_e32 v112, v112
	v_mov_b32_e32 v120, v113
	v_mul_f32_e32 v119, v119, v126
	v_mul_f32_e32 v118, v118, v119
	v_add_f32_e32 v112, 1.0, v112
	v_rcp_f32_e32 v125, v112
	v_pk_fma_f32 v[112:113], v[84:85], v[176:177], v[120:121] op_sel_hi:[1,0,1] neg_lo:[1,0,0] neg_hi:[1,0,0]
	v_cvt_f32_i32_e32 v26, v26
	v_pk_fma_f32 v[112:113], v[112:113], v[178:179], v[88:89] op_sel_hi:[1,0,1]
	v_mul_f32_e32 v117, v117, v125
	v_mul_f32_e32 v120, 0xbfb8aa3b, v113
	v_exp_f32_e32 v120, v120
	v_mul_f32_e32 v119, v116, v117
	v_mov_b32_e32 v117, v122
	v_mov_b32_e32 v122, v115
	v_add_f32_e32 v116, 1.0, v120
	v_rcp_f32_e32 v120, v116
	v_mov_b32_e32 v116, v114
	v_pk_fma_f32 v[116:117], v[142:143], v[176:177], v[116:117] op_sel_hi:[1,0,1] neg_lo:[1,0,0] neg_hi:[1,0,0]
	v_cvt_f32_i32_e32 v19, v19
	v_pk_fma_f32 v[116:117], v[116:117], v[178:179], v[162:163] op_sel_hi:[1,0,1]
	v_mul_f32_e32 v113, v113, v120
	v_mul_f32_e32 v114, 0xbfb8aa3b, v117
	v_exp_f32_e32 v121, v114
	v_pk_fma_f32 v[114:115], v[86:87], v[176:177], v[122:123] op_sel_hi:[1,0,1] neg_lo:[1,0,0] neg_hi:[1,0,0]
	v_mul_f32_e32 v113, v112, v113
	v_pk_fma_f32 v[114:115], v[114:115], v[178:179], v[90:91] op_sel_hi:[1,0,1]
	v_add_f32_e32 v120, 1.0, v121
	v_mul_f32_e32 v122, 0xbfb8aa3b, v115
	v_exp_f32_e32 v122, v122
	v_rcp_f32_e32 v120, v120
	v_cvt_f32_i32_e32 v18, v18
	v_pk_mul_f32 v[26:27], v[26:27], s[20:21] op_sel_hi:[1,0]
	v_add_f32_e32 v121, 1.0, v122
	v_rcp_f32_e32 v121, v121
	v_mul_f32_e32 v112, v117, v120
	v_mul_f32_e32 v116, v116, v112
	v_med3_f32 v117, v127, s62, v173
	v_mul_f32_e32 v112, v115, v121
	v_mul_f32_e32 v114, v114, v112
	v_med3_f32 v115, v161, s62, v173
	v_mov_b32_e32 v112, 0
; __device__ __forceinline__ u32x4 pack8bf(const f32x4 a, const f32x4 b) { u32x4 w; w.x = cvt_pk_bf16(a[0], a[1]); w.y = cvt_pk_bf16(a[2], a[3]); w.z = cvt_pk_bf16(b[0], b[1]); w.w = cvt_pk_bf16(b[2], b[3]); return w; }
; __device__ __forceinline__ void ln_stats(const float* st, int row, float& mu, float& rs) { const f32x2 s = *(const f32x2*)(st + 2 * (size_t)row); mu = s[0] * (1.0f / DM); rs = 1.0f / sqrtf(s[1] * (1.0f / DM) - mu * mu + LN_EPS); }
;     __device__ __forceinline__ void operator()(EPI_ARGS) const {
;     ...
;             for (int m = 0; m < 4; ++m) { const int row = row0 + ai * HALF + m * 16; f32x4 r[2];
;                 float mu = 0.f, rs = 1.f; if constexpr (FOLD) ln_stats(st, row, mu, rs);
; #pragma unroll
;                 for (int n = 0; n < 2; ++n) { f32x4 g = acc[ai][0][m][n], up = acc[ai][1][m][n];
;                     if constexpr (!PRE) { g = g * ascale; up = up * ascale; }
;                     if constexpr (FOLD) { g = (g - cg[n] * mu) * rs + dg[n]; up = (up - cu[n] * mu) * rs + du[n]; }
;                     if constexpr (!PRE) up = up * oscale;
; #pragma unroll
;                     for (int j = 0; j < 4; ++j) { const float e = __builtin_amdgcn_exp2f(g[j] * -1.4426950408889634f); r[n][j] = g[j] * __builtin_amdgcn_rcpf(1.0f + e) * up[j]; } }
;                 if constexpr (F8OUT) *(u32x2*)((unsigned char*)O + (size_t)row * ldc + col0) = pack8fp8(r[0], r[1]);
;                 else *(u32x4*)((bf16_t*)O + (size_t)row * ldc + col0) = pack8bf(r[0], r[1]); }
	v_cvt_pk_fp8_f32 v112, v115, v117
	v_med3_f32 v117, v118, s62, v173
	v_med3_f32 v118, v119, s62, v173
	v_med3_f32 v119, v113, s62, v173
	v_mov_b32_e32 v113, 0
	v_cvt_pk_fp8_f32 v113, v118, v119
	v_med3_f32 v115, v124, s62, v173
	v_cvt_pk_fp8_f32 v112, v115, v117 op_sel:[0,0,1]
	v_med3_f32 v115, v116, s62, v173
	v_med3_f32 v114, v114, s62, v173
	v_cvt_pk_fp8_f32 v113, v115, v114 op_sel:[0,0,1]
	v_mad_i64_i32 v[114:115], s[4:5], v174, s63, v[164:165]
	v_lshl_add_u64 v[114:115], v[114:115], 0, v[128:129]
	global_store_dwordx2 v[114:115], v[112:113], off
	v_or_b32_e32 v112, 32, v160
	v_ashrrev_i32_e32 v113, 31, v112
	v_lshl_add_u64 v[114:115], v[112:113], 3, s[14:15]
	v_mov_b32_e32 v114, v228
	v_mov_b32_e32 v115, v229
	v_pk_mul_f32 v[18:19], v[18:19], s[24:25] op_sel_hi:[1,0]
	v_cvt_f32_i32_e32 v13, v13
	v_cvt_f32_i32_e32 v12, v12
	v_cvt_f32_i32_e32 v5, v5
	v_cvt_f32_i32_e32 v4, v4
	v_cvt_f32_i32_e32 v15, v15
	v_pk_mul_f32 v[12:13], v[12:13], s[20:21] op_sel_hi:[1,0]
	v_cvt_f32_i32_e32 v14, v14
	v_pk_mul_f32 v[4:5], v[4:5], s[24:25] op_sel_hi:[1,0]
	v_cvt_f32_i32_e32 v7, v7
	v_cvt_f32_i32_e32 v6, v6
	v_pk_mul_f32 v[14:15], v[14:15], s[20:21] op_sel_hi:[1,0]
	v_cvt_f32_i32_e32 v9, v9
	v_cvt_f32_i32_e32 v8, v8
	v_pk_mul_f32 v[6:7], v[6:7], s[24:25] op_sel_hi:[1,0]
	v_cvt_f32_i32_e32 v1, v1
	v_cvt_f32_i32_e32 v0, v0
	v_pk_mul_f32 v[8:9], v[8:9], s[20:21] op_sel_hi:[1,0]
	v_cvt_f32_i32_e32 v11, v11
	v_cvt_f32_i32_e32 v10, v10
	v_pk_mul_f32 v[0:1], v[0:1], s[24:25] op_sel_hi:[1,0]
	v_cvt_f32_i32_e32 v3, v3
	v_cvt_f32_i32_e32 v2, v2
	v_pk_mul_f32 v[10:11], v[10:11], s[20:21] op_sel_hi:[1,0]
	v_pk_mul_f32 v[2:3], v[2:3], s[24:25] op_sel_hi:[1,0]
	v_pk_mul_f32 v[114:115], v[114:115], s[26:27] op_sel_hi:[1,0]
	s_nop 0
	v_fma_f32 v113, -v114, v114, v115
	v_add_f32_e32 v113, 0x3727c5ac, v113
	v_rsq_f32_e32 v242, v113
	s_nop 1
	s_nop 0
	s_nop 0
	s_nop 1
	s_nop 1
	s_nop 0
	v_mov_b32_e32 v118, v92
	v_mov_b32_e32 v119, v108
	v_mov_b32_e32 v116, v242
	v_pk_fma_f32 v[118:119], v[136:137], v[114:115], v[118:119] op_sel_hi:[1,0,1] neg_lo:[1,0,0] neg_hi:[1,0,0]
	v_mov_b32_e32 v108, v93
	v_pk_fma_f32 v[118:119], v[118:119], v[116:117], v[134:135] op_sel_hi:[1,0,1]
	s_nop 0
	v_mul_f32_e32 v92, 0xbfb8aa3b, v119
	v_exp_f32_e32 v113, v92
	v_pk_fma_f32 v[92:93], v[96:97], v[114:115], v[108:109] op_sel_hi:[1,0,1] neg_lo:[1,0,0] neg_hi:[1,0,0]
	v_add_f32_e32 v109, 1.0, v113
	v_pk_fma_f32 v[92:93], v[92:93], v[116:117], v[100:101] op_sel_hi:[1,0,1]
	v_rcp_f32_e32 v109, v109
	v_mul_f32_e32 v108, 0xbfb8aa3b, v93
	v_exp_f32_e32 v108, v108
	v_mul_f32_e32 v109, v119, v109
	v_mul_f32_e32 v113, v118, v109
	v_add_f32_e32 v108, 1.0, v108
	v_rcp_f32_e32 v108, v108
	v_mov_b32_e32 v109, v110
	v_mov_b32_e32 v110, v95
	v_mul_f32_e32 v93, v93, v108
	v_mov_b32_e32 v108, v94
	v_pk_fma_f32 v[108:109], v[132:133], v[114:115], v[108:109] op_sel_hi:[1,0,1] neg_lo:[1,0,0] neg_hi:[1,0,0]
	s_nop 0
	v_pk_fma_f32 v[108:109], v[108:109], v[116:117], v[130:131] op_sel_hi:[1,0,1]
	s_nop 0
	v_mul_f32_e32 v94, 0xbfb8aa3b, v109
	v_exp_f32_e32 v117, v94
	v_pk_fma_f32 v[94:95], v[98:99], v[114:115], v[110:111] op_sel_hi:[1,0,1] neg_lo:[1,0,0] neg_hi:[1,0,0]
	v_mul_f32_e32 v111, v92, v93
	v_mov_b32_e32 v93, v104
	v_pk_fma_f32 v[94:95], v[94:95], v[116:117], v[102:103] op_sel_hi:[1,0,1]
	v_add_f32_e32 v92, 1.0, v117
	v_mul_f32_e32 v110, 0xbfb8aa3b, v95
	v_exp_f32_e32 v110, v110
	v_rcp_f32_e32 v117, v92
	v_add_f32_e32 v92, 1.0, v110
	v_rcp_f32_e32 v110, v92
	v_mov_b32_e32 v92, v80
	v_pk_fma_f32 v[92:93], v[138:139], v[114:115], v[92:93] op_sel_hi:[1,0,1] neg_lo:[1,0,0] neg_hi:[1,0,0]
	v_mul_f32_e32 v104, v109, v117
	v_pk_fma_f32 v[92:93], v[92:93], v[116:117], v[140:141] op_sel_hi:[1,0,1]
	v_mul_f32_e32 v108, v108, v104
	v_mul_f32_e32 v80, 0xbfb8aa3b, v93
	v_exp_f32_e32 v80, v80
	v_mov_b32_e32 v104, v81
	v_mul_f32_e32 v95, v95, v110
	v_mul_f32_e32 v94, v94, v95
	v_add_f32_e32 v80, 1.0, v80
	v_rcp_f32_e32 v109, v80
	v_pk_fma_f32 v[80:81], v[84:85], v[114:115], v[104:105] op_sel_hi:[1,0,1] neg_lo:[1,0,0] neg_hi:[1,0,0]
	v_mul_f32_e32 v93, v93, v109
	v_pk_fma_f32 v[80:81], v[80:81], v[116:117], v[88:89] op_sel_hi:[1,0,1]
	v_mul_f32_e32 v95, v92, v93
	v_mul_f32_e32 v104, 0xbfb8aa3b, v81
	v_exp_f32_e32 v104, v104
	v_mov_b32_e32 v93, v106
	v_mov_b32_e32 v106, v83
	v_add_f32_e32 v92, 1.0, v104
	v_rcp_f32_e32 v104, v92
	v_mov_b32_e32 v92, v82
	v_pk_fma_f32 v[92:93], v[142:143], v[114:115], v[92:93] op_sel_hi:[1,0,1] neg_lo:[1,0,0] neg_hi:[1,0,0]
	v_mul_f32_e32 v81, v81, v104
	v_pk_fma_f32 v[92:93], v[92:93], v[116:117], v[162:163] op_sel_hi:[1,0,1]
	v_mul_f32_e32 v81, v80, v81
	v_mul_f32_e32 v82, 0xbfb8aa3b, v93
	v_exp_f32_e32 v105, v82
	v_pk_fma_f32 v[82:83], v[86:87], v[114:115], v[106:107] op_sel_hi:[1,0,1] neg_lo:[1,0,0] neg_hi:[1,0,0]
	v_add_f32_e32 v104, 1.0, v105
	v_pk_fma_f32 v[82:83], v[82:83], v[116:117], v[90:91] op_sel_hi:[1,0,1]
	v_rcp_f32_e32 v104, v104
	v_mul_f32_e32 v106, 0xbfb8aa3b, v83
	v_exp_f32_e32 v106, v106
	v_mul_f32_e32 v80, v93, v104
	v_mul_f32_e32 v92, v92, v80
	v_add_f32_e32 v105, 1.0, v106
	v_rcp_f32_e32 v105, v105
	v_med3_f32 v93, v111, s62, v173
	v_mul_f32_e32 v80, v83, v105
	v_mul_f32_e32 v82, v82, v80
	v_med3_f32 v83, v113, s62, v173
	v_mov_b32_e32 v80, 0
	v_cvt_pk_fp8_f32 v80, v83, v93
	v_med3_f32 v93, v94, s62, v173
	v_med3_f32 v94, v95, s62, v173
	v_med3_f32 v95, v81, s62, v173
	v_mov_b32_e32 v81, 0
	v_cvt_pk_fp8_f32 v81, v94, v95
	v_med3_f32 v83, v108, s62, v173
	v_cvt_pk_fp8_f32 v80, v83, v93 op_sel:[0,0,1]
	v_med3_f32 v83, v92, s62, v173
	v_med3_f32 v82, v82, s62, v173
	v_cvt_pk_fp8_f32 v81, v83, v82 op_sel:[0,0,1]
	v_mad_i64_i32 v[82:83], s[4:5], v112, s63, v[164:165]
; __device__ __forceinline__ u32x4 pack8bf(const f32x4 a, const f32x4 b) { u32x4 w; w.x = cvt_pk_bf16(a[0], a[1]); w.y = cvt_pk_bf16(a[2], a[3]); w.z = cvt_pk_bf16(b[0], b[1]); w.w = cvt_pk_bf16(b[2], b[3]); return w; }
; __device__ __forceinline__ void ln_stats(const float* st, int row, float& mu, float& rs) { const f32x2 s = *(const f32x2*)(st + 2 * (size_t)row); mu = s[0] * (1.0f / DM); rs = 1.0f / sqrtf(s[1] * (1.0f / DM) - mu * mu + LN_EPS); }
;     __device__ __forceinline__ void operator()(EPI_ARGS) const {
;     ...
;             for (int m = 0; m < 4; ++m) { const int row = row0 + ai * HALF + m * 16; f32x4 r[2];
;                 float mu = 0.f, rs = 1.f; if constexpr (FOLD) ln_stats(st, row, mu, rs);
; #pragma unroll
;                 for (int n = 0; n < 2; ++n) { f32x4 g = acc[ai][0][m][n], up = acc[ai][1][m][n];
;                     if constexpr (!PRE) { g = g * ascale; up = up * ascale; }
;                     if constexpr (FOLD) { g = (g - cg[n] * mu) * rs + dg[n]; up = (up - cu[n] * mu) * rs + du[n]; }
;                     if constexpr (!PRE) up = up * oscale;
; #pragma unroll
;                     for (int j = 0; j < 4; ++j) { const float e = __builtin_amdgcn_exp2f(g[j] * -1.4426950408889634f); r[n][j] = g[j] * __builtin_amdgcn_rcpf(1.0f + e) * up[j]; } }
;                 if constexpr (F8OUT) *(u32x2*)((unsigned char*)O + (size_t)row * ldc + col0) = pack8fp8(r[0], r[1]);
;                 else *(u32x4*)((bf16_t*)O + (size_t)row * ldc + col0) = pack8bf(r[0], r[1]); }
	v_lshl_add_u64 v[82:83], v[82:83], 0, v[128:129]
	global_store_dwordx2 v[82:83], v[80:81], off
	v_or_b32_e32 v80, 48, v160
	v_ashrrev_i32_e32 v81, 31, v80
	v_lshl_add_u64 v[82:83], v[80:81], 3, s[14:15]
	v_mov_b32_e32 v82, v230
	v_mov_b32_e32 v83, v231
	v_pk_mul_f32 v[82:83], v[82:83], s[26:27] op_sel_hi:[1,0]
	s_nop 0
	v_fma_f32 v81, -v82, v82, v83
	v_add_f32_e32 v81, 0x3727c5ac, v81
	v_rsq_f32_e32 v242, v81
	s_nop 1
	s_nop 0
	s_nop 0
	s_nop 1
	s_nop 1
	s_nop 0
	v_mov_b32_e32 v94, v68
	v_mov_b32_e32 v95, v76
	v_mov_b32_e32 v92, v242
	v_pk_fma_f32 v[94:95], v[136:137], v[82:83], v[94:95] op_sel_hi:[1,0,1] neg_lo:[1,0,0] neg_hi:[1,0,0]
	v_mov_b32_e32 v76, v69
	v_pk_fma_f32 v[94:95], v[94:95], v[92:93], v[134:135] op_sel_hi:[1,0,1]
	s_nop 0
	v_mul_f32_e32 v68, 0xbfb8aa3b, v95
	v_exp_f32_e32 v81, v68
	v_pk_fma_f32 v[68:69], v[96:97], v[82:83], v[76:77] op_sel_hi:[1,0,1] neg_lo:[1,0,0] neg_hi:[1,0,0]
	v_add_f32_e32 v77, 1.0, v81
	v_pk_fma_f32 v[68:69], v[68:69], v[92:93], v[100:101] op_sel_hi:[1,0,1]
	v_rcp_f32_e32 v77, v77
	v_mul_f32_e32 v76, 0xbfb8aa3b, v69
	v_exp_f32_e32 v76, v76
	v_mul_f32_e32 v77, v95, v77
	v_mul_f32_e32 v81, v94, v77
	v_add_f32_e32 v76, 1.0, v76
	v_rcp_f32_e32 v76, v76
	v_mov_b32_e32 v77, v78
	v_mov_b32_e32 v78, v71
	v_mul_f32_e32 v69, v69, v76
	v_mov_b32_e32 v76, v70
	v_pk_fma_f32 v[76:77], v[132:133], v[82:83], v[76:77] op_sel_hi:[1,0,1] neg_lo:[1,0,0] neg_hi:[1,0,0]
	s_nop 0
	v_pk_fma_f32 v[76:77], v[76:77], v[92:93], v[130:131] op_sel_hi:[1,0,1]
	s_nop 0
	v_mul_f32_e32 v70, 0xbfb8aa3b, v77
	v_exp_f32_e32 v93, v70
	v_pk_fma_f32 v[70:71], v[98:99], v[82:83], v[78:79] op_sel_hi:[1,0,1] neg_lo:[1,0,0] neg_hi:[1,0,0]
	v_mul_f32_e32 v79, v68, v69
	v_mov_b32_e32 v69, v72
	v_pk_fma_f32 v[70:71], v[70:71], v[92:93], v[102:103] op_sel_hi:[1,0,1]
	v_add_f32_e32 v68, 1.0, v93
	v_mul_f32_e32 v78, 0xbfb8aa3b, v71
	v_exp_f32_e32 v78, v78
	v_rcp_f32_e32 v93, v68
	v_add_f32_e32 v68, 1.0, v78
	v_rcp_f32_e32 v78, v68
	v_mov_b32_e32 v68, v64
	v_pk_fma_f32 v[68:69], v[138:139], v[82:83], v[68:69] op_sel_hi:[1,0,1] neg_lo:[1,0,0] neg_hi:[1,0,0]
	v_mul_f32_e32 v72, v77, v93
	v_pk_fma_f32 v[68:69], v[68:69], v[92:93], v[140:141] op_sel_hi:[1,0,1]
	v_mul_f32_e32 v76, v76, v72
	v_mul_f32_e32 v64, 0xbfb8aa3b, v69
	v_exp_f32_e32 v64, v64
	v_mov_b32_e32 v72, v65
	v_mul_f32_e32 v71, v71, v78
	v_mul_f32_e32 v70, v70, v71
	v_add_f32_e32 v64, 1.0, v64
	v_rcp_f32_e32 v77, v64
	v_pk_fma_f32 v[64:65], v[84:85], v[82:83], v[72:73] op_sel_hi:[1,0,1] neg_lo:[1,0,0] neg_hi:[1,0,0]
	v_mul_f32_e32 v69, v69, v77
	v_pk_fma_f32 v[64:65], v[64:65], v[92:93], v[88:89] op_sel_hi:[1,0,1]
	v_mul_f32_e32 v71, v68, v69
	v_mul_f32_e32 v72, 0xbfb8aa3b, v65
	v_exp_f32_e32 v72, v72
	v_mov_b32_e32 v69, v74
	v_mov_b32_e32 v74, v67
	v_add_f32_e32 v68, 1.0, v72
	v_rcp_f32_e32 v72, v68
	v_mov_b32_e32 v68, v66
	v_pk_fma_f32 v[68:69], v[142:143], v[82:83], v[68:69] op_sel_hi:[1,0,1] neg_lo:[1,0,0] neg_hi:[1,0,0]
	v_mul_f32_e32 v65, v65, v72
	v_pk_fma_f32 v[68:69], v[68:69], v[92:93], v[162:163] op_sel_hi:[1,0,1]
	v_mul_f32_e32 v65, v64, v65
	v_mul_f32_e32 v66, 0xbfb8aa3b, v69
	v_exp_f32_e32 v73, v66
	v_pk_fma_f32 v[66:67], v[86:87], v[82:83], v[74:75] op_sel_hi:[1,0,1] neg_lo:[1,0,0] neg_hi:[1,0,0]
	v_add_f32_e32 v72, 1.0, v73
	v_pk_fma_f32 v[66:67], v[66:67], v[92:93], v[90:91] op_sel_hi:[1,0,1]
	v_rcp_f32_e32 v72, v72
	v_mul_f32_e32 v74, 0xbfb8aa3b, v67
	v_exp_f32_e32 v74, v74
	v_mul_f32_e32 v64, v69, v72
	v_mul_f32_e32 v68, v68, v64
	v_add_f32_e32 v73, 1.0, v74
	v_rcp_f32_e32 v73, v73
	v_med3_f32 v69, v79, s62, v173
	v_mul_f32_e32 v64, v67, v73
	v_mul_f32_e32 v66, v66, v64
	v_med3_f32 v67, v81, s62, v173
	v_mov_b32_e32 v64, 0
	v_cvt_pk_fp8_f32 v64, v67, v69
	v_med3_f32 v69, v70, s62, v173
	v_med3_f32 v70, v71, s62, v173
	v_med3_f32 v71, v65, s62, v173
	v_mov_b32_e32 v65, 0
	v_cvt_pk_fp8_f32 v65, v70, v71
	v_med3_f32 v67, v76, s62, v173
	v_cvt_pk_fp8_f32 v64, v67, v69 op_sel:[0,0,1]
	v_med3_f32 v67, v68, s62, v173
	v_med3_f32 v66, v66, s62, v173
	v_cvt_pk_fp8_f32 v65, v67, v66 op_sel:[0,0,1]
	v_mad_i64_i32 v[66:67], s[4:5], v80, s63, v[164:165]
	v_lshl_add_u64 v[66:67], v[66:67], 0, v[128:129]
	global_store_dwordx2 v[66:67], v[64:65], off
	v_add_u32_e32 v64, 0x80, v160
	v_ashrrev_i32_e32 v65, 31, v64
	v_lshl_add_u64 v[66:67], v[64:65], 3, s[14:15]
	v_mov_b32_e32 v66, v232
	v_mov_b32_e32 v67, v233
	v_pk_mul_f32 v[66:67], v[66:67], s[26:27] op_sel_hi:[1,0]
	s_nop 0
	v_fma_f32 v65, -v66, v66, v67
	v_add_f32_e32 v65, 0x3727c5ac, v65
	v_rsq_f32_e32 v242, v65
	s_nop 1
	s_nop 0
	s_nop 0
	s_nop 1
	s_nop 1
	s_nop 0
	v_mov_b32_e32 v70, v52
	v_mov_b32_e32 v71, v60
	v_mov_b32_e32 v68, v242
	v_pk_fma_f32 v[70:71], v[136:137], v[66:67], v[70:71] op_sel_hi:[1,0,1] neg_lo:[1,0,0] neg_hi:[1,0,0]
	v_mov_b32_e32 v60, v53
	v_pk_fma_f32 v[70:71], v[70:71], v[68:69], v[134:135] op_sel_hi:[1,0,1]
	s_nop 0
	v_mul_f32_e32 v52, 0xbfb8aa3b, v71
	v_exp_f32_e32 v65, v52
	v_pk_fma_f32 v[52:53], v[96:97], v[66:67], v[60:61] op_sel_hi:[1,0,1] neg_lo:[1,0,0] neg_hi:[1,0,0]
	v_add_f32_e32 v61, 1.0, v65
	v_pk_fma_f32 v[52:53], v[52:53], v[68:69], v[100:101] op_sel_hi:[1,0,1]
	v_rcp_f32_e32 v61, v61
	v_mul_f32_e32 v60, 0xbfb8aa3b, v53
	v_exp_f32_e32 v60, v60
	v_mul_f32_e32 v61, v71, v61
	v_mul_f32_e32 v65, v70, v61
	v_add_f32_e32 v60, 1.0, v60
	v_rcp_f32_e32 v60, v60
	v_mov_b32_e32 v61, v62
	v_mov_b32_e32 v62, v55
	v_mul_f32_e32 v53, v53, v60
	v_mov_b32_e32 v60, v54
	v_pk_fma_f32 v[60:61], v[132:133], v[66:67], v[60:61] op_sel_hi:[1,0,1] neg_lo:[1,0,0] neg_hi:[1,0,0]
	s_nop 0
	v_pk_fma_f32 v[60:61], v[60:61], v[68:69], v[130:131] op_sel_hi:[1,0,1]
	s_nop 0
	v_mul_f32_e32 v54, 0xbfb8aa3b, v61
	v_exp_f32_e32 v69, v54
; __device__ __forceinline__ u32x4 pack8bf(const f32x4 a, const f32x4 b) { u32x4 w; w.x = cvt_pk_bf16(a[0], a[1]); w.y = cvt_pk_bf16(a[2], a[3]); w.z = cvt_pk_bf16(b[0], b[1]); w.w = cvt_pk_bf16(b[2], b[3]); return w; }
; __device__ __forceinline__ void ln_stats(const float* st, int row, float& mu, float& rs) { const f32x2 s = *(const f32x2*)(st + 2 * (size_t)row); mu = s[0] * (1.0f / DM); rs = 1.0f / sqrtf(s[1] * (1.0f / DM) - mu * mu + LN_EPS); }
;     __device__ __forceinline__ void operator()(EPI_ARGS) const {
;     ...
;             for (int m = 0; m < 4; ++m) { const int row = row0 + ai * HALF + m * 16; f32x4 r[2];
;                 float mu = 0.f, rs = 1.f; if constexpr (FOLD) ln_stats(st, row, mu, rs);
; #pragma unroll
;                 for (int n = 0; n < 2; ++n) { f32x4 g = acc[ai][0][m][n], up = acc[ai][1][m][n];
;                     if constexpr (!PRE) { g = g * ascale; up = up * ascale; }
;                     if constexpr (FOLD) { g = (g - cg[n] * mu) * rs + dg[n]; up = (up - cu[n] * mu) * rs + du[n]; }
;                     if constexpr (!PRE) up = up * oscale;
; #pragma unroll
;                     for (int j = 0; j < 4; ++j) { const float e = __builtin_amdgcn_exp2f(g[j] * -1.4426950408889634f); r[n][j] = g[j] * __builtin_amdgcn_rcpf(1.0f + e) * up[j]; } }
;                 if constexpr (F8OUT) *(u32x2*)((unsigned char*)O + (size_t)row * ldc + col0) = pack8fp8(r[0], r[1]);
;                 else *(u32x4*)((bf16_t*)O + (size_t)row * ldc + col0) = pack8bf(r[0], r[1]); }
	v_pk_fma_f32 v[54:55], v[98:99], v[66:67], v[62:63] op_sel_hi:[1,0,1] neg_lo:[1,0,0] neg_hi:[1,0,0]
	v_mul_f32_e32 v63, v52, v53
	v_mov_b32_e32 v53, v56
	v_pk_fma_f32 v[54:55], v[54:55], v[68:69], v[102:103] op_sel_hi:[1,0,1]
	v_add_f32_e32 v52, 1.0, v69
	v_mul_f32_e32 v62, 0xbfb8aa3b, v55
	v_exp_f32_e32 v62, v62
	v_rcp_f32_e32 v69, v52
	v_add_f32_e32 v52, 1.0, v62
	v_rcp_f32_e32 v62, v52
	v_mov_b32_e32 v52, v48
	v_pk_fma_f32 v[52:53], v[138:139], v[66:67], v[52:53] op_sel_hi:[1,0,1] neg_lo:[1,0,0] neg_hi:[1,0,0]
	v_mul_f32_e32 v56, v61, v69
	v_pk_fma_f32 v[52:53], v[52:53], v[68:69], v[140:141] op_sel_hi:[1,0,1]
	v_mul_f32_e32 v60, v60, v56
	v_mul_f32_e32 v48, 0xbfb8aa3b, v53
	v_exp_f32_e32 v48, v48
	v_mov_b32_e32 v56, v49
	v_mul_f32_e32 v55, v55, v62
	v_mul_f32_e32 v54, v54, v55
	v_add_f32_e32 v48, 1.0, v48
	v_rcp_f32_e32 v61, v48
	v_pk_fma_f32 v[48:49], v[84:85], v[66:67], v[56:57] op_sel_hi:[1,0,1] neg_lo:[1,0,0] neg_hi:[1,0,0]
	v_mul_f32_e32 v53, v53, v61
	v_pk_fma_f32 v[48:49], v[48:49], v[68:69], v[88:89] op_sel_hi:[1,0,1]
	v_mul_f32_e32 v55, v52, v53
	v_mul_f32_e32 v56, 0xbfb8aa3b, v49
	v_exp_f32_e32 v56, v56
	v_mov_b32_e32 v53, v58
	v_mov_b32_e32 v58, v51
	v_add_f32_e32 v52, 1.0, v56
	v_rcp_f32_e32 v56, v52
	v_mov_b32_e32 v52, v50
	v_pk_fma_f32 v[52:53], v[142:143], v[66:67], v[52:53] op_sel_hi:[1,0,1] neg_lo:[1,0,0] neg_hi:[1,0,0]
	v_mul_f32_e32 v49, v49, v56
	v_pk_fma_f32 v[52:53], v[52:53], v[68:69], v[162:163] op_sel_hi:[1,0,1]
	v_mul_f32_e32 v49, v48, v49
	v_mul_f32_e32 v50, 0xbfb8aa3b, v53
	v_exp_f32_e32 v57, v50
	v_pk_fma_f32 v[50:51], v[86:87], v[66:67], v[58:59] op_sel_hi:[1,0,1] neg_lo:[1,0,0] neg_hi:[1,0,0]
	v_add_f32_e32 v56, 1.0, v57
	v_pk_fma_f32 v[50:51], v[50:51], v[68:69], v[90:91] op_sel_hi:[1,0,1]
	v_rcp_f32_e32 v56, v56
	v_mul_f32_e32 v58, 0xbfb8aa3b, v51
	v_exp_f32_e32 v58, v58
	v_mul_f32_e32 v48, v53, v56
	v_mul_f32_e32 v52, v52, v48
	v_add_f32_e32 v57, 1.0, v58
	v_rcp_f32_e32 v57, v57
	v_med3_f32 v53, v63, s62, v173
	v_mul_f32_e32 v48, v51, v57
	v_mul_f32_e32 v50, v50, v48
	v_med3_f32 v51, v65, s62, v173
	v_mov_b32_e32 v48, 0
	v_cvt_pk_fp8_f32 v48, v51, v53
	v_med3_f32 v53, v54, s62, v173
	v_med3_f32 v54, v55, s62, v173
	v_med3_f32 v55, v49, s62, v173
	v_mov_b32_e32 v49, 0
	v_cvt_pk_fp8_f32 v49, v54, v55
	v_med3_f32 v51, v60, s62, v173
	v_cvt_pk_fp8_f32 v48, v51, v53 op_sel:[0,0,1]
	v_med3_f32 v51, v52, s62, v173
	v_med3_f32 v50, v50, s62, v173
	v_cvt_pk_fp8_f32 v49, v51, v50 op_sel:[0,0,1]
	v_mad_i64_i32 v[50:51], s[4:5], v64, s63, v[164:165]
	v_lshl_add_u64 v[50:51], v[50:51], 0, v[128:129]
	global_store_dwordx2 v[50:51], v[48:49], off
	v_add_u32_e32 v48, 0x90, v160
	v_ashrrev_i32_e32 v49, 31, v48
	v_lshl_add_u64 v[50:51], v[48:49], 3, s[14:15]
	v_mov_b32_e32 v50, v234
	v_mov_b32_e32 v51, v235
	v_pk_mul_f32 v[50:51], v[50:51], s[26:27] op_sel_hi:[1,0]
	s_nop 0
	v_fma_f32 v49, -v50, v50, v51
	v_add_f32_e32 v49, 0x3727c5ac, v49
	v_rsq_f32_e32 v242, v49
	s_nop 1
	s_nop 0
	s_nop 0
	s_nop 1
	s_nop 1
	s_nop 0
	v_mov_b32_e32 v54, v36
	v_mov_b32_e32 v55, v44
	v_mov_b32_e32 v52, v242
	v_pk_fma_f32 v[54:55], v[136:137], v[50:51], v[54:55] op_sel_hi:[1,0,1] neg_lo:[1,0,0] neg_hi:[1,0,0]
	v_mov_b32_e32 v44, v37
	v_pk_fma_f32 v[54:55], v[54:55], v[52:53], v[134:135] op_sel_hi:[1,0,1]
	s_nop 0
	v_mul_f32_e32 v36, 0xbfb8aa3b, v55
	v_exp_f32_e32 v49, v36
	v_pk_fma_f32 v[36:37], v[96:97], v[50:51], v[44:45] op_sel_hi:[1,0,1] neg_lo:[1,0,0] neg_hi:[1,0,0]
	v_add_f32_e32 v45, 1.0, v49
	v_pk_fma_f32 v[36:37], v[36:37], v[52:53], v[100:101] op_sel_hi:[1,0,1]
	v_rcp_f32_e32 v45, v45
	v_mul_f32_e32 v44, 0xbfb8aa3b, v37
	v_exp_f32_e32 v44, v44
	v_mul_f32_e32 v45, v55, v45
	v_mul_f32_e32 v49, v54, v45
	v_add_f32_e32 v44, 1.0, v44
	v_rcp_f32_e32 v44, v44
	v_mov_b32_e32 v45, v46
	v_mov_b32_e32 v46, v39
	v_mul_f32_e32 v37, v37, v44
	v_mov_b32_e32 v44, v38
	v_pk_fma_f32 v[44:45], v[132:133], v[50:51], v[44:45] op_sel_hi:[1,0,1] neg_lo:[1,0,0] neg_hi:[1,0,0]
	s_nop 0
	v_pk_fma_f32 v[44:45], v[44:45], v[52:53], v[130:131] op_sel_hi:[1,0,1]
	s_nop 0
	v_mul_f32_e32 v38, 0xbfb8aa3b, v45
	v_exp_f32_e32 v53, v38
	v_pk_fma_f32 v[38:39], v[98:99], v[50:51], v[46:47] op_sel_hi:[1,0,1] neg_lo:[1,0,0] neg_hi:[1,0,0]
	v_mul_f32_e32 v47, v36, v37
	v_mov_b32_e32 v37, v40
	v_pk_fma_f32 v[38:39], v[38:39], v[52:53], v[102:103] op_sel_hi:[1,0,1]
	v_add_f32_e32 v36, 1.0, v53
	v_mul_f32_e32 v46, 0xbfb8aa3b, v39
	v_exp_f32_e32 v46, v46
	v_rcp_f32_e32 v53, v36
	v_add_f32_e32 v36, 1.0, v46
	v_rcp_f32_e32 v46, v36
	v_mov_b32_e32 v36, v32
	v_pk_fma_f32 v[36:37], v[138:139], v[50:51], v[36:37] op_sel_hi:[1,0,1] neg_lo:[1,0,0] neg_hi:[1,0,0]
	v_mul_f32_e32 v40, v45, v53
	v_pk_fma_f32 v[36:37], v[36:37], v[52:53], v[140:141] op_sel_hi:[1,0,1]
	v_mul_f32_e32 v44, v44, v40
	v_mul_f32_e32 v32, 0xbfb8aa3b, v37
	v_exp_f32_e32 v32, v32
	v_mov_b32_e32 v40, v33
	v_mul_f32_e32 v39, v39, v46
	v_mul_f32_e32 v38, v38, v39
	v_add_f32_e32 v32, 1.0, v32
	v_rcp_f32_e32 v45, v32
	v_pk_fma_f32 v[32:33], v[84:85], v[50:51], v[40:41] op_sel_hi:[1,0,1] neg_lo:[1,0,0] neg_hi:[1,0,0]
	v_mul_f32_e32 v37, v37, v45
	v_pk_fma_f32 v[32:33], v[32:33], v[52:53], v[88:89] op_sel_hi:[1,0,1]
	v_mul_f32_e32 v39, v36, v37
	v_mul_f32_e32 v40, 0xbfb8aa3b, v33
	v_exp_f32_e32 v40, v40
	v_mov_b32_e32 v37, v42
	v_mov_b32_e32 v42, v35
	v_add_f32_e32 v36, 1.0, v40
	v_rcp_f32_e32 v40, v36
	v_mov_b32_e32 v36, v34
	v_pk_fma_f32 v[36:37], v[142:143], v[50:51], v[36:37] op_sel_hi:[1,0,1] neg_lo:[1,0,0] neg_hi:[1,0,0]
	v_mul_f32_e32 v33, v33, v40
	v_pk_fma_f32 v[36:37], v[36:37], v[52:53], v[162:163] op_sel_hi:[1,0,1]
	v_mul_f32_e32 v33, v32, v33
	v_mul_f32_e32 v34, 0xbfb8aa3b, v37
	v_exp_f32_e32 v41, v34
; __device__ __forceinline__ u32x4 pack8bf(const f32x4 a, const f32x4 b) { u32x4 w; w.x = cvt_pk_bf16(a[0], a[1]); w.y = cvt_pk_bf16(a[2], a[3]); w.z = cvt_pk_bf16(b[0], b[1]); w.w = cvt_pk_bf16(b[2], b[3]); return w; }
; __device__ __forceinline__ void ln_stats(const float* st, int row, float& mu, float& rs) { const f32x2 s = *(const f32x2*)(st + 2 * (size_t)row); mu = s[0] * (1.0f / DM); rs = 1.0f / sqrtf(s[1] * (1.0f / DM) - mu * mu + LN_EPS); }
;     __device__ __forceinline__ void operator()(EPI_ARGS) const {
;     ...
;             for (int m = 0; m < 4; ++m) { const int row = row0 + ai * HALF + m * 16; f32x4 r[2];
;                 float mu = 0.f, rs = 1.f; if constexpr (FOLD) ln_stats(st, row, mu, rs);
; #pragma unroll
;                 for (int n = 0; n < 2; ++n) { f32x4 g = acc[ai][0][m][n], up = acc[ai][1][m][n];
;                     if constexpr (!PRE) { g = g * ascale; up = up * ascale; }
;                     if constexpr (FOLD) { g = (g - cg[n] * mu) * rs + dg[n]; up = (up - cu[n] * mu) * rs + du[n]; }
;                     if constexpr (!PRE) up = up * oscale;
; #pragma unroll
;                     for (int j = 0; j < 4; ++j) { const float e = __builtin_amdgcn_exp2f(g[j] * -1.4426950408889634f); r[n][j] = g[j] * __builtin_amdgcn_rcpf(1.0f + e) * up[j]; } }
;                 if constexpr (F8OUT) *(u32x2*)((unsigned char*)O + (size_t)row * ldc + col0) = pack8fp8(r[0], r[1]);
;                 else *(u32x4*)((bf16_t*)O + (size_t)row * ldc + col0) = pack8bf(r[0], r[1]); }
	v_pk_fma_f32 v[34:35], v[86:87], v[50:51], v[42:43] op_sel_hi:[1,0,1] neg_lo:[1,0,0] neg_hi:[1,0,0]
	v_add_f32_e32 v40, 1.0, v41
	v_pk_fma_f32 v[34:35], v[34:35], v[52:53], v[90:91] op_sel_hi:[1,0,1]
	v_rcp_f32_e32 v40, v40
	v_mul_f32_e32 v42, 0xbfb8aa3b, v35
	v_exp_f32_e32 v42, v42
	v_mul_f32_e32 v32, v37, v40
	v_mul_f32_e32 v36, v36, v32
	v_add_f32_e32 v41, 1.0, v42
	v_rcp_f32_e32 v41, v41
	v_med3_f32 v37, v47, s62, v173
	v_mul_f32_e32 v32, v35, v41
	v_mul_f32_e32 v34, v34, v32
	v_med3_f32 v35, v49, s62, v173
	v_mov_b32_e32 v32, 0
	v_cvt_pk_fp8_f32 v32, v35, v37
	v_med3_f32 v37, v38, s62, v173
	v_med3_f32 v38, v39, s62, v173
	v_med3_f32 v39, v33, s62, v173
	v_mov_b32_e32 v33, 0
	v_cvt_pk_fp8_f32 v33, v38, v39
	v_med3_f32 v35, v44, s62, v173
	v_cvt_pk_fp8_f32 v32, v35, v37 op_sel:[0,0,1]
	v_med3_f32 v35, v36, s62, v173
	v_med3_f32 v34, v34, s62, v173
	v_cvt_pk_fp8_f32 v33, v35, v34 op_sel:[0,0,1]
	v_mad_i64_i32 v[34:35], s[4:5], v48, s63, v[164:165]
	v_lshl_add_u64 v[34:35], v[34:35], 0, v[128:129]
	global_store_dwordx2 v[34:35], v[32:33], off
	v_add_u32_e32 v32, 0xa0, v160
	v_ashrrev_i32_e32 v33, 31, v32
	v_lshl_add_u64 v[34:35], v[32:33], 3, s[14:15]
	v_mov_b32_e32 v34, v236
	v_mov_b32_e32 v35, v237
	v_pk_mul_f32 v[34:35], v[34:35], s[26:27] op_sel_hi:[1,0]
	s_nop 0
	v_fma_f32 v33, -v34, v34, v35
	v_add_f32_e32 v33, 0x3727c5ac, v33
	v_rsq_f32_e32 v242, v33
	s_nop 1
	s_nop 0
	s_nop 0
	s_nop 1
	s_nop 1
	s_nop 0
	v_mov_b32_e32 v38, v20
	v_mov_b32_e32 v39, v28
	v_mov_b32_e32 v36, v242
	v_pk_fma_f32 v[38:39], v[136:137], v[34:35], v[38:39] op_sel_hi:[1,0,1] neg_lo:[1,0,0] neg_hi:[1,0,0]
	v_mov_b32_e32 v28, v21
	v_pk_fma_f32 v[38:39], v[38:39], v[36:37], v[134:135] op_sel_hi:[1,0,1]
	s_nop 0
	v_mul_f32_e32 v20, 0xbfb8aa3b, v39
	v_exp_f32_e32 v33, v20
	v_pk_fma_f32 v[20:21], v[96:97], v[34:35], v[28:29] op_sel_hi:[1,0,1] neg_lo:[1,0,0] neg_hi:[1,0,0]
	v_add_f32_e32 v29, 1.0, v33
	v_pk_fma_f32 v[20:21], v[20:21], v[36:37], v[100:101] op_sel_hi:[1,0,1]
	v_rcp_f32_e32 v29, v29
	v_mul_f32_e32 v28, 0xbfb8aa3b, v21
	v_exp_f32_e32 v28, v28
	v_mul_f32_e32 v29, v39, v29
	v_mul_f32_e32 v33, v38, v29
	v_add_f32_e32 v28, 1.0, v28
	v_rcp_f32_e32 v28, v28
	v_mov_b32_e32 v29, v30
	v_mov_b32_e32 v30, v23
	v_mul_f32_e32 v21, v21, v28
	v_mov_b32_e32 v28, v22
	v_pk_fma_f32 v[28:29], v[132:133], v[34:35], v[28:29] op_sel_hi:[1,0,1] neg_lo:[1,0,0] neg_hi:[1,0,0]
	s_nop 0
	v_pk_fma_f32 v[28:29], v[28:29], v[36:37], v[130:131] op_sel_hi:[1,0,1]
	s_nop 0
	v_mul_f32_e32 v22, 0xbfb8aa3b, v29
	v_exp_f32_e32 v37, v22
	v_pk_fma_f32 v[22:23], v[98:99], v[34:35], v[30:31] op_sel_hi:[1,0,1] neg_lo:[1,0,0] neg_hi:[1,0,0]
	v_mul_f32_e32 v31, v20, v21
	v_mov_b32_e32 v21, v24
	v_pk_fma_f32 v[22:23], v[22:23], v[36:37], v[102:103] op_sel_hi:[1,0,1]
	v_add_f32_e32 v20, 1.0, v37
	v_mul_f32_e32 v30, 0xbfb8aa3b, v23
	v_exp_f32_e32 v30, v30
	v_rcp_f32_e32 v37, v20
	v_add_f32_e32 v20, 1.0, v30
	v_rcp_f32_e32 v30, v20
	v_mov_b32_e32 v20, v16
	v_pk_fma_f32 v[20:21], v[138:139], v[34:35], v[20:21] op_sel_hi:[1,0,1] neg_lo:[1,0,0] neg_hi:[1,0,0]
	v_mul_f32_e32 v24, v29, v37
	v_pk_fma_f32 v[20:21], v[20:21], v[36:37], v[140:141] op_sel_hi:[1,0,1]
	v_mul_f32_e32 v28, v28, v24
	v_mul_f32_e32 v16, 0xbfb8aa3b, v21
	v_exp_f32_e32 v16, v16
	v_mov_b32_e32 v24, v17
	v_mul_f32_e32 v23, v23, v30
	v_mul_f32_e32 v22, v22, v23
	v_add_f32_e32 v16, 1.0, v16
	v_rcp_f32_e32 v29, v16
	v_pk_fma_f32 v[16:17], v[84:85], v[34:35], v[24:25] op_sel_hi:[1,0,1] neg_lo:[1,0,0] neg_hi:[1,0,0]
	v_mul_f32_e32 v21, v21, v29
	v_pk_fma_f32 v[16:17], v[16:17], v[36:37], v[88:89] op_sel_hi:[1,0,1]
	v_mul_f32_e32 v23, v20, v21
	v_mul_f32_e32 v24, 0xbfb8aa3b, v17
	v_exp_f32_e32 v24, v24
	v_mov_b32_e32 v21, v26
	v_mov_b32_e32 v26, v19
	v_add_f32_e32 v20, 1.0, v24
	v_rcp_f32_e32 v24, v20
	v_mov_b32_e32 v20, v18
	v_pk_fma_f32 v[20:21], v[142:143], v[34:35], v[20:21] op_sel_hi:[1,0,1] neg_lo:[1,0,0] neg_hi:[1,0,0]
	v_mul_f32_e32 v17, v17, v24
	v_pk_fma_f32 v[20:21], v[20:21], v[36:37], v[162:163] op_sel_hi:[1,0,1]
	v_mul_f32_e32 v17, v16, v17
	v_mul_f32_e32 v18, 0xbfb8aa3b, v21
	v_exp_f32_e32 v25, v18
	v_pk_fma_f32 v[18:19], v[86:87], v[34:35], v[26:27] op_sel_hi:[1,0,1] neg_lo:[1,0,0] neg_hi:[1,0,0]
	v_add_f32_e32 v24, 1.0, v25
	v_pk_fma_f32 v[18:19], v[18:19], v[36:37], v[90:91] op_sel_hi:[1,0,1]
	v_rcp_f32_e32 v24, v24
	v_mul_f32_e32 v26, 0xbfb8aa3b, v19
	v_exp_f32_e32 v26, v26
	v_mul_f32_e32 v16, v21, v24
	v_mul_f32_e32 v20, v20, v16
	v_add_f32_e32 v25, 1.0, v26
	v_rcp_f32_e32 v25, v25
	v_med3_f32 v21, v31, s62, v173
	v_mul_f32_e32 v16, v19, v25
	v_mul_f32_e32 v18, v18, v16
	v_med3_f32 v19, v33, s62, v173
; #define PG8_BAR __builtin_amdgcn_s_barrier()
; __device__ __forceinline__ u32x4 pack8bf(const f32x4 a, const f32x4 b) { u32x4 w; w.x = cvt_pk_bf16(a[0], a[1]); w.y = cvt_pk_bf16(a[2], a[3]); w.z = cvt_pk_bf16(b[0], b[1]); w.w = cvt_pk_bf16(b[2], b[3]); return w; }
; __device__ __forceinline__ void ln_stats(const float* st, int row, float& mu, float& rs) { const f32x2 s = *(const f32x2*)(st + 2 * (size_t)row); mu = s[0] * (1.0f / DM); rs = 1.0f / sqrtf(s[1] * (1.0f / DM) - mu * mu + LN_EPS); }
;     ...
;         if (wr == 0) PG8_BAR;
;         E(acc, cur, wr, wc, fr, fq);
;         if (!has_next) break;
; #pragma unroll
;         for (int a = 0; a < 2; ++a)
; #pragma unroll
;             for (int b = 0; b < 2; ++b)
; #pragma unroll
;                 for (int m = 0; m < 4; ++m)
; #pragma unroll
;                     for (int n = 0; n < 2; ++n) acc[a][b][m][n] = (f32x4){0.f, 0.f, 0.f, 0.f};
;         cur = nxt; cA = nA; cB = nB; ++ui;
;         if (wr == 1) PG8_BAR;
;     __device__ __forceinline__ void operator()(EPI_ARGS) const {
;     ...
;             for (int m = 0; m < 4; ++m) { const int row = row0 + ai * HALF + m * 16; f32x4 r[2];
;                 float mu = 0.f, rs = 1.f; if constexpr (FOLD) ln_stats(st, row, mu, rs);
; #pragma unroll
;                 for (int n = 0; n < 2; ++n) { f32x4 g = acc[ai][0][m][n], up = acc[ai][1][m][n];
;                     if constexpr (!PRE) { g = g * ascale; up = up * ascale; }
;                     if constexpr (FOLD) { g = (g - cg[n] * mu) * rs + dg[n]; up = (up - cu[n] * mu) * rs + du[n]; }
;                     if constexpr (!PRE) up = up * oscale;
; #pragma unroll
;                     for (int j = 0; j < 4; ++j) { const float e = __builtin_amdgcn_exp2f(g[j] * -1.4426950408889634f); r[n][j] = g[j] * __builtin_amdgcn_rcpf(1.0f + e) * up[j]; } }
;                 if constexpr (F8OUT) *(u32x2*)((unsigned char*)O + (size_t)row * ldc + col0) = pack8fp8(r[0], r[1]);
;                 else *(u32x4*)((bf16_t*)O + (size_t)row * ldc + col0) = pack8bf(r[0], r[1]); }
	v_mov_b32_e32 v16, 0
	v_cvt_pk_fp8_f32 v16, v19, v21
	v_med3_f32 v21, v22, s62, v173
	v_med3_f32 v22, v23, s62, v173
	v_med3_f32 v23, v17, s62, v173
	v_mov_b32_e32 v17, 0
	v_cvt_pk_fp8_f32 v17, v22, v23
	v_med3_f32 v19, v28, s62, v173
	v_cvt_pk_fp8_f32 v16, v19, v21 op_sel:[0,0,1]
	v_med3_f32 v19, v20, s62, v173
	v_med3_f32 v18, v18, s62, v173
	v_cvt_pk_fp8_f32 v17, v19, v18 op_sel:[0,0,1]
	v_mad_i64_i32 v[18:19], s[4:5], v32, s63, v[164:165]
	v_lshl_add_u64 v[18:19], v[18:19], 0, v[128:129]
	global_store_dwordx2 v[18:19], v[16:17], off
	v_add_u32_e32 v16, 0xb0, v160
	v_ashrrev_i32_e32 v17, 31, v16
	v_lshl_add_u64 v[18:19], v[16:17], 3, s[14:15]
	v_mov_b32_e32 v18, v238
	v_mov_b32_e32 v19, v239
	v_pk_mul_f32 v[18:19], v[18:19], s[26:27] op_sel_hi:[1,0]
	s_nop 0
	v_fma_f32 v17, -v18, v18, v19
	v_add_f32_e32 v17, 0x3727c5ac, v17
	v_rsq_f32_e32 v242, v17
	s_nop 1
	s_nop 0
	s_nop 0
	s_nop 1
	s_nop 1
	s_nop 0
	v_mov_b32_e32 v22, v4
	v_mov_b32_e32 v23, v12
	v_mov_b32_e32 v20, v242
	v_pk_fma_f32 v[22:23], v[136:137], v[18:19], v[22:23] op_sel_hi:[1,0,1] neg_lo:[1,0,0] neg_hi:[1,0,0]
	v_mov_b32_e32 v12, v5
	v_pk_fma_f32 v[22:23], v[22:23], v[20:21], v[134:135] op_sel_hi:[1,0,1]
	s_andn2_b64 vcc, exec, s[2:3]
	v_mul_f32_e32 v4, 0xbfb8aa3b, v23
	v_exp_f32_e32 v17, v4
	v_pk_fma_f32 v[4:5], v[96:97], v[18:19], v[12:13] op_sel_hi:[1,0,1] neg_lo:[1,0,0] neg_hi:[1,0,0]
	s_mov_b64 s[2:3], -1
	v_pk_fma_f32 v[4:5], v[4:5], v[20:21], v[100:101] op_sel_hi:[1,0,1]
	v_add_f32_e32 v13, 1.0, v17
	v_mul_f32_e32 v12, 0xbfb8aa3b, v5
	v_exp_f32_e32 v12, v12
	v_rcp_f32_e32 v13, v13
	v_add_f32_e32 v12, 1.0, v12
	v_rcp_f32_e32 v12, v12
	v_mul_f32_e32 v13, v23, v13
	v_mul_f32_e32 v17, v22, v13
	v_mov_b32_e32 v13, v14
	v_mul_f32_e32 v5, v5, v12
	v_mov_b32_e32 v12, v6
	v_pk_fma_f32 v[12:13], v[132:133], v[18:19], v[12:13] op_sel_hi:[1,0,1] neg_lo:[1,0,0] neg_hi:[1,0,0]
	v_mov_b32_e32 v14, v7
	v_pk_fma_f32 v[12:13], v[12:13], v[20:21], v[130:131] op_sel_hi:[1,0,1]
	s_nop 0
	v_mul_f32_e32 v6, 0xbfb8aa3b, v13
	v_exp_f32_e32 v21, v6
	v_pk_fma_f32 v[6:7], v[98:99], v[18:19], v[14:15] op_sel_hi:[1,0,1] neg_lo:[1,0,0] neg_hi:[1,0,0]
	v_mul_f32_e32 v15, v4, v5
	v_mov_b32_e32 v5, v8
	v_pk_fma_f32 v[6:7], v[6:7], v[20:21], v[102:103] op_sel_hi:[1,0,1]
	v_add_f32_e32 v4, 1.0, v21
	v_mul_f32_e32 v14, 0xbfb8aa3b, v7
	v_exp_f32_e32 v14, v14
	v_rcp_f32_e32 v21, v4
	v_add_f32_e32 v4, 1.0, v14
	v_rcp_f32_e32 v14, v4
	v_mov_b32_e32 v4, v0
	v_pk_fma_f32 v[4:5], v[138:139], v[18:19], v[4:5] op_sel_hi:[1,0,1] neg_lo:[1,0,0] neg_hi:[1,0,0]
	v_mul_f32_e32 v8, v13, v21
	v_pk_fma_f32 v[4:5], v[4:5], v[20:21], v[140:141] op_sel_hi:[1,0,1]
	v_mul_f32_e32 v12, v12, v8
	v_mul_f32_e32 v0, 0xbfb8aa3b, v5
	v_exp_f32_e32 v0, v0
	v_mov_b32_e32 v8, v1
	v_mul_f32_e32 v7, v7, v14
	v_mul_f32_e32 v6, v6, v7
	v_add_f32_e32 v0, 1.0, v0
	v_rcp_f32_e32 v13, v0
	v_pk_fma_f32 v[0:1], v[84:85], v[18:19], v[8:9] op_sel_hi:[1,0,1] neg_lo:[1,0,0] neg_hi:[1,0,0]
	v_mul_f32_e32 v5, v5, v13
	v_pk_fma_f32 v[0:1], v[0:1], v[20:21], v[88:89] op_sel_hi:[1,0,1]
	v_mul_f32_e32 v7, v4, v5
	v_mul_f32_e32 v8, 0xbfb8aa3b, v1
	v_exp_f32_e32 v8, v8
	v_mov_b32_e32 v5, v10
	v_mov_b32_e32 v10, v3
	v_add_f32_e32 v4, 1.0, v8
	v_rcp_f32_e32 v8, v4
	v_mov_b32_e32 v4, v2
	v_pk_fma_f32 v[4:5], v[142:143], v[18:19], v[4:5] op_sel_hi:[1,0,1] neg_lo:[1,0,0] neg_hi:[1,0,0]
	v_mul_f32_e32 v1, v1, v8
	v_pk_fma_f32 v[4:5], v[4:5], v[20:21], v[162:163] op_sel_hi:[1,0,1]
	v_mul_f32_e32 v1, v0, v1
	v_mul_f32_e32 v2, 0xbfb8aa3b, v5
	v_exp_f32_e32 v9, v2
	v_pk_fma_f32 v[2:3], v[86:87], v[18:19], v[10:11] op_sel_hi:[1,0,1] neg_lo:[1,0,0] neg_hi:[1,0,0]
	v_add_f32_e32 v8, 1.0, v9
	v_pk_fma_f32 v[2:3], v[2:3], v[20:21], v[90:91] op_sel_hi:[1,0,1]
	v_rcp_f32_e32 v8, v8
	v_mul_f32_e32 v10, 0xbfb8aa3b, v3
	v_exp_f32_e32 v10, v10
	v_mul_f32_e32 v0, v5, v8
	v_mul_f32_e32 v4, v4, v0
	v_add_f32_e32 v9, 1.0, v10
	v_rcp_f32_e32 v9, v9
	v_med3_f32 v5, v15, s62, v173
	v_mul_f32_e32 v0, v3, v9
	v_mul_f32_e32 v2, v2, v0
	v_med3_f32 v3, v17, s62, v173
	v_mov_b32_e32 v0, 0
	v_cvt_pk_fp8_f32 v0, v3, v5
	v_med3_f32 v5, v6, s62, v173
	v_med3_f32 v6, v7, s62, v173
	v_med3_f32 v7, v1, s62, v173
	v_mov_b32_e32 v1, 0
	v_cvt_pk_fp8_f32 v1, v6, v7
	v_med3_f32 v3, v12, s62, v173
	v_cvt_pk_fp8_f32 v0, v3, v5 op_sel:[0,0,1]
	v_med3_f32 v3, v4, s62, v173
	v_med3_f32 v2, v2, s62, v173
	v_cvt_pk_fp8_f32 v1, v3, v2 op_sel:[0,0,1]
	v_mad_i64_i32 v[2:3], s[4:5], v16, s63, v[164:165]
	v_lshl_add_u64 v[2:3], v[2:3], 0, v[128:129]
	global_store_dwordx2 v[2:3], v[0:1], off
	s_cbranch_vccnz .LBB0_3772
	s_andn2_b64 vcc, exec, s[6:7]
	s_cbranch_vccnz .LBB0_3771
	s_barrier
	s_branch .LBB0_3771
